# v25
# baseline (speedup 1.0000x reference)
; template <int EPI>
; __device__ __forceinline__ void gemm_phase(const u16* __restrict__ A, const u16* __restrict__ Bt, const int K,
;                                            const int nN, char* shm, const EpiArgs& ea) {
;     ...
;   const int wid = __builtin_amdgcn_readfirstlane(tid >> 6);
;   const int lane = tid & 63;
;   const int wr = wid >> 2, wc = wid & 3, fr = lane & 15, fq = lane >> 4;
.LBB0_14:
	v_readfirstlane_b32 s98, v174
	s_nop 3
	s_cmp_lt_u32 s98, 0x100
	s_cbranch_scc0 .Lprio_skip
	s_setprio 1
